# stack of the individually validated small edits: barrier without relay, aligned per-XCD GEMM tile windows, MLA prologue second tile hoisted, FFN-up MFMA chains in place, DPP wave sums
# speedup vs baseline: 1.0028x; 1.0028x over previous
;     __device__ __forceinline__ void load(int t) {
;         unsigned tid = this->tid; asm volatile("" : "+v"(tid));
;         const char* knt = kn + (size_t)t * (64 * 2048); const char* krt = kr + (size_t)t * (64 * 128); const char* vtt = vt + (size_t)t * 128;
; #pragma unroll
;         for (int i = 0; i < 2; ++i) { const unsigned c = tid + 512u * i; rk[i] = *(const u32x4*)(knt + ((c >> 4) * 2048u + (c & 15u) * 16u)); }
;         rk[2] = *(const u32x4*)(krt + ((tid >> 3) * 128u + (tid & 7u) * 16u));
; #pragma unroll
;         for (int i = 0; i < 2; ++i) { const unsigned c = tid + 512u * i; rv[i] = *(const u32x4*)(vtt + ((c >> 3) * (unsigned)(VT_LD * 2) + (c & 7u) * 16u)); }
; template <int DQK, bool BIAS, class Loader>
; __device__ __forceinline__ void attn_unit(const int tid, LAS unsigned char* lds, Loader& L, const bf16_t* qptr, bool wave_active, int t0, int t1, int wt0, int wt1, int nkeys, int qpos, int kpos0, bf16_t* optr) {
;     ...
;     for (int ks = 0; ks < NKS; ++ks) qf[ks] = *(const bf16x8*)(qptr + ks * 16 + hi * 8);
;     f32x16 o0, o1, o2, o3;
; #pragma unroll
;     for (int r = 0; r < 16; ++r) { o0[r] = 0.f; o1[r] = 0.f; o2[r] = 0.f; o3[r] = 0.f; }
;     float m_run = -1e30f, l_run = 0.f;
;     L.load(t0); L.store(lds, lds + AT_VBUF0); if (t0 + 1 < t1) L.load(t0 + 1); __syncthreads();
.LBB0_4927:
	s_xor_b64 s[58:59], s[14:15], -1
	s_and_b64 s[14:15], s[14:15], exec
	s_cselect_b32 s18, s86, s65
	v_lshl_add_u32 v206, s18, 8, v187
	s_movk_i32 s14, 0xc00
	v_mad_i64_i32 v[0:1], s[14:15], v206, s14, v[202:203]
	s_waitcnt vmcnt(45)
	v_mov_b32_e32 v16, v184
	global_load_dwordx4 v[156:159], v[0:1], off
	global_load_dwordx4 v[152:155], v[0:1], off offset:32
	global_load_dwordx4 v[148:151], v[0:1], off offset:64
	global_load_dwordx4 v[144:147], v[0:1], off offset:96
	global_load_dwordx4 v[140:143], v[0:1], off offset:128
	global_load_dwordx4 v[136:139], v[0:1], off offset:160
	global_load_dwordx4 v[132:135], v[0:1], off offset:192
	global_load_dwordx4 v[128:131], v[0:1], off offset:224
	global_load_dwordx4 v[124:127], v[0:1], off offset:256
	global_load_dwordx4 v[120:123], v[0:1], off offset:288
	global_load_dwordx4 v[116:119], v[0:1], off offset:320
	global_load_dwordx4 v[112:115], v[0:1], off offset:352
	v_mov_b32_e32 v20, v184
	v_lshlrev_b32_e32 v4, 4, v16
	v_lshlrev_b32_e32 v0, 7, v16
	v_and_b32_e32 v1, 0xf0, v4
	v_lshrrev_b32_e32 v9, 3, v16
	v_and_or_b32 v0, v0, s3, v1
	s_waitcnt vmcnt(56)
	v_and_b32_e32 v17, 0x70, v4
	v_mul_lo_u32 v9, v9, s21
	v_add_u32_e32 v8, 0x10000, v0
	v_or_b32_e32 v12, v9, v17
	global_load_dwordx4 v[160:163], v0, s[54:55]
	s_nop 0
	global_load_dwordx4 v[0:3], v0, s[48:49]
	s_nop 0
	global_load_dwordx4 v[168:171], v4, s[56:57]
	s_nop 0
	global_load_dwordx4 v[4:7], v4, s[50:51]
	s_nop 0
	global_load_dwordx4 v[164:167], v8, s[54:55]
	s_nop 0
	global_load_dwordx4 v[8:11], v8, s[48:49]
	s_nop 0
	global_load_dwordx4 v[172:175], v12, s[52:53] offset:128
	s_nop 0
	global_load_dwordx4 v[12:15], v12, s[52:53]
	v_add_u32_e32 v16, 0x200, v16
	v_lshrrev_b32_e32 v16, 3, v16
	v_mul_lo_u32 v16, v16, s21
	v_or_b32_e32 v16, v16, v17
	global_load_dwordx4 v[176:179], v16, s[52:53] offset:128
	s_nop 0
	global_load_dwordx4 v[16:19], v16, s[52:53]
	s_waitcnt vmcnt(63)
	v_mov_b32_e32 v23, v184
	v_lshlrev_b32_e32 v21, 4, v20
	s_waitcnt vmcnt(62)
	v_lshrrev_b32_e32 v24, 4, v20
	v_add_u32_e32 v22, 0x200, v20
	s_waitcnt vmcnt(60)
	v_lshrrev_b32_e32 v26, 3, v20
	v_and_b32_e32 v20, 0xf0, v21
	v_lshrrev_b32_e32 v27, 4, v22
	v_and_b32_e32 v21, 0x70, v21
	v_lshrrev_b32_e32 v25, 3, v22
	v_add_u32_e32 v20, 0, v20
	v_mul_lo_u32 v28, v26, s33
	v_add_u32_e32 v22, 0, v21
	s_waitcnt vmcnt(59)
	v_mul_lo_u32 v29, v25, s33
	v_mad_u64_u32 v[24:25], s[14:15], v24, s64, v[20:21]
	v_mad_u64_u32 v[20:21], s[14:15], v27, s64, v[20:21]
	v_mad_u64_u32 v[26:27], s[14:15], v26, s64, v[22:23]
	v_add3_u32 v21, v22, v28, s2
	v_add3_u32 v22, v22, v29, s2
	s_waitcnt vmcnt(57)
	v_mov_b32_e32 v33, v32
	v_mov_b32_e32 v46, v32
	s_waitcnt vmcnt(48)
	v_mov_b32_e32 v47, v32
	s_lshl_b32 s14, s18, 2
	v_mov_b32_e32 v34, v32
	v_mov_b32_e32 v35, v32
	v_mov_b32_e32 v36, v32
	v_mov_b32_e32 v37, v32
	v_mov_b32_e32 v38, v32
	v_mov_b32_e32 v39, v32
	v_mov_b32_e32 v40, v32
	v_mov_b32_e32 v41, v32
	v_mov_b32_e32 v42, v32
	v_mov_b32_e32 v43, v32
	v_mov_b32_e32 v44, v32
	v_mov_b32_e32 v45, v32
	v_mov_b64_e32 v[78:79], v[46:47]
	s_waitcnt vmcnt(40)
	v_mov_b64_e32 v[62:63], v[46:47]
	s_add_i32 s15, s14, s76
	s_add_i32 s26, s14, 4
	s_or_b32 s14, s14, 3
	s_mov_b32 s87, 0
	v_mov_b32_e32 v215, 0
	v_mov_b32_e32 v216, 0xf149f2ca
	s_mov_b64 s[18:19], s[30:31]
	s_mov_b64 s[60:61], s[16:17]
	s_mov_b64 s[62:63], s[0:1]
	v_mov_b64_e32 v[76:77], v[44:45]
	v_mov_b64_e32 v[74:75], v[42:43]
	v_mov_b64_e32 v[72:73], v[40:41]
	v_mov_b64_e32 v[70:71], v[38:39]
	v_mov_b64_e32 v[68:69], v[36:37]
	v_mov_b64_e32 v[66:67], v[34:35]
	v_mov_b64_e32 v[64:65], v[32:33]
	v_mov_b64_e32 v[60:61], v[44:45]
	v_mov_b64_e32 v[58:59], v[42:43]
	v_mov_b64_e32 v[56:57], v[40:41]
	v_mov_b64_e32 v[54:55], v[38:39]
	v_mov_b64_e32 v[52:53], v[36:37]
	v_mov_b64_e32 v[50:51], v[34:35]
	s_waitcnt vmcnt(8)
	ds_write_b128 v24, v[0:3]
	s_waitcnt vmcnt(4)
	ds_write_b128 v20, v[8:11]
	ds_write_b128 v26, v[4:7] offset:256
	s_waitcnt vmcnt(2)
	ds_write2_b64 v21, v[12:13], v[14:15] offset1:1
	s_waitcnt vmcnt(0)
	ds_write2_b64 v22, v[16:17], v[18:19] offset1:1
	v_mov_b64_e32 v[48:49], v[32:33]
	v_mov_b64_e32 v[16:17], v[32:33]
	v_mov_b64_e32 v[0:1], v[32:33]
	v_mov_b64_e32 v[18:19], v[34:35]
	v_mov_b64_e32 v[20:21], v[36:37]
	v_mov_b64_e32 v[22:23], v[38:39]
	v_mov_b64_e32 v[24:25], v[40:41]
	v_mov_b64_e32 v[26:27], v[42:43]
	v_mov_b64_e32 v[28:29], v[44:45]
	v_mov_b64_e32 v[30:31], v[46:47]
	v_mov_b64_e32 v[2:3], v[34:35]
	v_mov_b64_e32 v[4:5], v[36:37]
	v_mov_b64_e32 v[6:7], v[38:39]
	v_mov_b64_e32 v[8:9], v[40:41]
	v_mov_b64_e32 v[10:11], v[42:43]
	v_mov_b64_e32 v[12:13], v[44:45]
	v_mov_b64_e32 v[14:15], v[46:47]
	s_waitcnt lgkmcnt(0)
	s_barrier
	s_branch .LBB0_4930
